# P2 token loop: loads with addresses known at the top of the iteration (q/kv latent rows, k-rope, position, norm gains) issued up front into dead registers; their serialised vmcnt(0) waits removed; on
# speedup vs baseline: 1.0038x; 1.0005x over previous
; __device__ __forceinline__ float bf2f(bf16 h) { return __uint_as_float((unsigned)h << 16); }
; __device__ __forceinline__ v4u pack8f(const float (&f)[8]) { v4u o; o.x = pk2(f[0], f[1]); o.y = pk2(f[2], f[3]); o.z = pk2(f[4], f[5]); o.w = pk2(f[6], f[7]); return o; }
; __global__ void __launch_bounds__(NWAVES * 64, 2) fwd_kernel(Args a) {
;     ...
;         for (int m = gw; m < MTOK; m += NGW) {
;             const int t = m & (SEQL - 1);
;             const bf16* zr = zconv + (size_t)m * 3072;
; #pragma unroll
;             for (int ch = 0; ch < 2; ++ch) {
;                 const int c = ch * 512 + lane * 8;
;                 const v4u z4 = {0u, 0u, 0u, 0u};
;                 const v4u zb = *(const v4u*)(zr + c), zc0 = *(const v4u*)(zr + 1024 + c), zv0 = *(const v4u*)(zr + 2048 + c);
;                 const v4u zc1 = t >= 1 ? *(const v4u*)(zr - 3072 + 1024 + c) : z4, zv1 = t >= 1 ? *(const v4u*)(zr - 3072 + 2048 + c) : z4;
;                 const v4u zc2 = t >= 2 ? *(const v4u*)(zr - 6144 + 1024 + c) : z4, zv2 = t >= 2 ? *(const v4u*)(zr - 6144 + 2048 + c) : z4;
;     ...
;                 const float kr = bf2f(zkr[(size_t)m * 64 + lane]); const float kss = wave_sum(kr * kr); if (lane == 0) krss[m] = kss;
;                 const float v = kr * gkr, pt = __shfl_xor(v, 32);
;                 krr[(size_t)m * 64 + lane] = lane < 32 ? v * cs - pt * sn : v * cs + pt * sn;
;             }
;             {
;                 const v4u ka = *(const v4u*)(zkv + (size_t)m * KVL + lane * 8);
;                 float fa[8]; unpack8(ka, fa); float s = 0.f;
; #pragma unroll
;                 for (int e = 0; e < 8; ++e) s += fa[e] * fa[e];
;                 const float r = rsqrtf(wave_sum(s) * (1.f / 512.f) + EPS);
;                 const f32x4 g0 = *(const f32x4*)(kvg + lane * 8), g1 = *(const f32x4*)(kvg + lane * 8 + 4);
;                 float oa[8] = {fa[0] * r * g0.x, fa[1] * r * g0.y, fa[2] * r * g0.z, fa[3] * r * g0.w, fa[4] * r * g1.x, fa[5] * r * g1.y, fa[6] * r * g1.z, fa[7] * r * g1.w};
;                 *(v4u*)(kvn + (size_t)m * KVL + lane * 8) = pack8f(oa);
;             }
.LBB0_263:
	s_or_b64 exec, exec, s[4:5]
	v_mul_f32_e32 v11, v67, v8
	ds_bpermute_b32 v12, v2, v11
	v_lshl_add_u64 v[18:19], s[30:31], 0, v[50:51]
	v_lshl_add_u64 v[8:9], s[30:31], 0, v[54:55]
	s_waitcnt lgkmcnt(1)
	s_waitcnt lgkmcnt(0)
	v_mul_f32_e32 v7, v7, v12
	v_cndmask_b32_e64 v7, v7, -v7, s[0:1]
	v_fmac_f32_e32 v7, v6, v11
	global_store_dword v[8:9], v7, off
	s_nop 0
	s_add_i32 s3, s3, s12
	s_add_u32 s20, s20, s26
	s_addc_u32 s21, s21, s27
	s_add_u32 s24, s24, s26
	s_addc_u32 s25, s25, s27
	v_lshl_add_u64 v[48:49], v[48:49], 0, s[36:37]
	v_lshl_add_u64 v[50:51], v[50:51], 0, s[38:39]
	v_lshl_add_u64 v[52:53], v[52:53], 0, s[40:41]
	v_lshl_add_u64 v[54:55], v[54:55], 0, s[46:47]
	v_lshl_add_u64 v[56:57], v[56:57], 0, s[40:41]
	v_lshl_add_u64 v[58:59], v[58:59], 0, s[48:49]
	v_lshl_add_u64 v[60:61], v[60:61], 0, s[48:49]
	s_cmpk_gt_i32 s3, 0x1fff
	v_lshl_add_u64 v[62:63], v[62:63], 0, s[54:55]
	v_and_b32_e32 v25, 0xffff0000, v196
	v_lshlrev_b32_e32 v24, 16, v196
	v_mul_f32_e32 v28, v25, v25
	v_lshlrev_b32_e32 v26, 16, v197
	v_fmac_f32_e32 v28, v24, v24
	v_and_b32_e32 v27, 0xffff0000, v197
	v_lshlrev_b32_e32 v6, 16, v198
	v_and_b32_e32 v7, 0xffff0000, v198
	v_fmac_f32_e32 v28, v26, v26
	v_pk_mul_f32 v[20:21], v[6:7], v[6:7]
	v_fmac_f32_e32 v28, v27, v27
	v_lshlrev_b32_e32 v8, 16, v199
	v_and_b32_e32 v9, 0xffff0000, v199
	v_add_f32_e32 v20, v28, v20
	v_pk_mul_f32 v[22:23], v[8:9], v[8:9]
	v_add_f32_e32 v20, v20, v21
	v_add_f32_e32 v20, v20, v22
	v_add_f32_e32 v20, v20, v23
	ds_bpermute_b32 v0, v0, v20
	s_waitcnt lgkmcnt(0)
	v_add_f32_e32 v0, v20, v0
	ds_bpermute_b32 v3, v3, v0
	s_waitcnt lgkmcnt(0)
	v_add_f32_e32 v0, v0, v3
	ds_bpermute_b32 v3, v4, v0
	v_add_co_u32_e32 v4, vcc, s60, v18
	s_waitcnt lgkmcnt(0)
	v_add_f32_e32 v0, v0, v3
	ds_bpermute_b32 v3, v5, v0
	v_addc_co_u32_e32 v5, vcc, 0, v19, vcc
	s_waitcnt lgkmcnt(0)
	v_add_f32_e32 v0, v0, v3
	ds_bpermute_b32 v1, v1, v0
	s_waitcnt lgkmcnt(0)
	v_add_f32_e32 v0, v0, v1
	ds_bpermute_b32 v1, v2, v0
	s_waitcnt lgkmcnt(0)
	v_add_f32_e32 v0, v0, v1
	v_fmamk_f32 v0, v0, 0x3b000000, v68
	v_mul_f32_e32 v1, 0x4b800000, v0
	v_cmp_gt_f32_e32 vcc, s34, v0
	s_nop 1
	v_cndmask_b32_e32 v0, v0, v1, vcc
	v_rsq_f32_e32 v0, v0
	s_nop 0
	v_mul_f32_e32 v1, 0x45800000, v0
	v_cndmask_b32_e32 v0, v0, v1, vcc
	v_mul_f32_e32 v1, v0, v24
	v_mul_f32_e32 v2, v0, v25
	v_mul_f32_e32 v3, v0, v26
	v_mul_f32_e32 v18, v0, v27
	v_mul_f32_e32 v6, v0, v6
	v_mul_f32_e32 v7, v0, v7
	v_mul_f32_e32 v8, v0, v8
	v_mul_f32_e32 v0, v0, v9
	v_mul_f32_e32 v1, v200, v1
	v_mul_f32_e32 v2, v201, v2
	v_mul_f32_e32 v3, v202, v3
	v_mul_f32_e32 v9, v203, v18
	v_mul_f32_e32 v6, v204, v6
	v_mul_f32_e32 v7, v205, v7
	v_mul_f32_e32 v8, v206, v8
	v_mul_f32_e32 v10, v207, v0
	v_cvt_pk_bf16_f32 v0, v1, v2
	v_cvt_pk_bf16_f32 v1, v3, v9
	v_cvt_pk_bf16_f32 v2, v6, v7
	v_cvt_pk_bf16_f32 v3, v8, v10
	global_store_dwordx4 v[4:5], v[0:3], off
	s_cbranch_scc1 .LBB0_285
.LBB0_264:
	s_add_u32 s100, s30, s33
	s_addc_u32 s101, s31, 0
	v_lshl_add_u64 v[208:209], s[100:101], 0, v[58:59]
	v_lshl_add_u64 v[210:211], s[100:101], 0, v[60:61]
	global_load_dwordx4 v[176:179], v[208:209], off
	global_load_dwordx2 v[180:181], v[210:211], off offset:1024
	global_load_dwordx4 v[184:187], v[32:33], off offset:16
	global_load_dwordx4 v[188:191], v[32:33], off
	global_load_dwordx4 v[192:195], v[34:35], off offset:2048
	global_load_dword v182, v31, s[20:21]
	v_lshl_add_u64 v[212:213], s[30:31], 0, v[52:53]
	global_load_ushort v183, v[212:213], off
	s_add_u32 s100, s30, 0x9e00000
	s_addc_u32 s101, s31, 0
	v_lshl_add_u64 v[214:215], s[100:101], 0, v[50:51]
	global_load_dwordx4 v[196:199], v[214:215], off
	global_load_dwordx4 v[200:203], v[36:37], off
	global_load_dwordx4 v[204:207], v[36:37], off offset:16
	v_lshl_add_u64 v[64:65], s[30:31], 0, v[62:63]
	v_add_co_u32_e32 v0, vcc, 0x6200000, v64
	s_and_b32 s61, s3, 0xfff
	s_nop 0
	v_addc_co_u32_e32 v1, vcc, 0, v65, vcc
	global_load_dwordx4 v[26:29], v[0:1], off
	global_load_dwordx4 v[2:5], v[0:1], off offset:2048
	v_add_co_u32_e32 v0, vcc, 0x6201000, v64
	s_cmp_lg_u32 s61, 0
	s_nop 0
	v_addc_co_u32_e32 v1, vcc, 0, v65, vcc
	global_load_dwordx4 v[6:9], v[0:1], off
	s_cselect_b64 s[6:7], -1, 0
	s_cmp_eq_u32 s61, 0
	s_cbranch_scc1 .LBB0_266
	v_add_co_u32_e32 v0, vcc, 0x61ff000, v64
	s_nop 1
	v_addc_co_u32_e32 v1, vcc, 0, v65, vcc
	global_load_dwordx4 v[10:13], v[0:1], off
	s_branch .LBB0_267

; __device__ __forceinline__ unsigned pk2(float lo, float hi) { return pg8::cvt_pk_bf16(lo, hi); }
; __global__ void __launch_bounds__(NWAVES * 64, 2) fwd_kernel(Args a) {
;     ...
;                 float fb[8], fc0[8], fv0[8], fc1[8], fv1[8], fc2[8], fv2[8], w0[8], w1[8], w2[8], o[8];
;                 unpack8(zb, fb); unpack8(zc0, fc0); unpack8(zv0, fv0); unpack8(zc1, fc1); unpack8(zv1, fv1); unpack8(zc2, fc2); unpack8(zv2, fv2);
;                 *(f32x4*)&w0[0] = *(const f32x4*)(cw + c); *(f32x4*)&w0[4] = *(const f32x4*)(cw + c + 4);
;                 *(f32x4*)&w1[0] = *(const f32x4*)(cw + 1024 + c); *(f32x4*)&w1[4] = *(const f32x4*)(cw + 1024 + c + 4);
;                 *(f32x4*)&w2[0] = *(const f32x4*)(cw + 2048 + c); *(f32x4*)&w2[4] = *(const f32x4*)(cw + 2048 + c + 4);
; #pragma unroll
;                 for (int e = 0; e < 8; ++e) o[e] = fb[e] * (w0[e] * (fc2[e] * fv2[e]) + w1[e] * (fc1[e] * fv1[e]) + w2[e] * (fc0[e] * fv0[e]));
;                 *(v4u*)(cm + (size_t)m * CONVD + c) = pack8f(o);
;             }
;             {
;                 const bf16* qr = zq + (size_t)m * QL;
;                 const v4u qa = *(const v4u*)(qr + lane * 8); const v2u qb2 = *(const v2u*)(qr + 512 + lane * 4);
;                 float fa[8]; unpack8(qa, fa);
;                 float fb4[4] = {__uint_as_float(qb2.x << 16), __uint_as_float(qb2.x & 0xffff0000u), __uint_as_float(qb2.y << 16), __uint_as_float(qb2.y & 0xffff0000u)};
;                 float s = 0.f;
; #pragma unroll
;                 for (int e = 0; e < 8; ++e) s += fa[e] * fa[e];
; #pragma unroll
;                 for (int e = 0; e < 4; ++e) s += fb4[e] * fb4[e];
;                 const float r = rsqrtf(wave_sum(s) * (1.f / 768.f) + EPS);
;                 const f32x4 g0 = *(const f32x4*)(qg + lane * 8), g1 = *(const f32x4*)(qg + lane * 8 + 4), g2 = *(const f32x4*)(qg + 512 + lane * 4);
;                 float oa[8] = {fa[0] * r * g0.x, fa[1] * r * g0.y, fa[2] * r * g0.z, fa[3] * r * g0.w, fa[4] * r * g1.x, fa[5] * r * g1.y, fa[6] * r * g1.z, fa[7] * r * g1.w};
;                 *(v4u*)(qn + (size_t)m * QL + lane * 8) = pack8f(oa);
;                 v2u ob; ob.x = pk2(fb4[0] * r * g2.x, fb4[1] * r * g2.y); ob.y = pk2(fb4[2] * r * g2.z, fb4[3] * r * g2.w);
;                 *(v2u*)(qn + (size_t)m * QL + 512 + lane * 4) = ob;
.LBB0_281:
	s_nop 0
	global_load_dwordx4 v[70:73], v[38:39], off offset:2048
	global_load_dwordx4 v[74:77], v[46:47], off
	global_load_dwordx4 v[78:81], v[38:39], off offset:2064
	global_load_dwordx4 v[82:85], v[46:47], off offset:16
	global_load_dwordx4 v[86:89], v[44:45], off
	global_load_dwordx4 v[90:93], v[44:45], off offset:16
	s_waitcnt vmcnt(8)
	v_lshlrev_b32_e32 v69, 16, v24
	v_and_b32_e32 v100, 0xffff0000, v24
	v_lshlrev_b32_e32 v101, 16, v25
	v_and_b32_e32 v102, 0xffff0000, v25
	v_lshlrev_b32_e32 v103, 16, v26
	v_and_b32_e32 v104, 0xffff0000, v26
	v_lshlrev_b32_e32 v105, 16, v27
	v_and_b32_e32 v106, 0xffff0000, v27
	s_waitcnt vmcnt(6)
	v_lshlrev_b32_e32 v108, 16, v0
	v_lshlrev_b32_e32 v24, 16, v12
	v_lshlrev_b32_e32 v25, 16, v4
	v_lshlrev_b32_e32 v26, 16, v20
	v_lshlrev_b32_e32 v27, 16, v8
	v_and_b32_e32 v110, 0xffff0000, v0
	v_and_b32_e32 v65, 0xffff0000, v4
	v_and_b32_e32 v64, 0xffff0000, v12
	v_and_b32_e32 v95, 0xffff0000, v8
	v_lshlrev_b32_e32 v111, 16, v1
	v_lshlrev_b32_e32 v96, 16, v13
	v_lshlrev_b32_e32 v97, 16, v5
	v_lshlrev_b32_e32 v99, 16, v9
	v_and_b32_e32 v114, 0xffff0000, v1
	v_and_b32_e32 v1, 0xffff0000, v5
	v_and_b32_e32 v0, 0xffff0000, v13
	v_and_b32_e32 v5, 0xffff0000, v9
	v_and_b32_e32 v4, 0xffff0000, v21
	v_lshlrev_b32_e32 v8, 16, v14
	v_lshlrev_b32_e32 v9, 16, v6
	v_lshlrev_b32_e32 v12, 16, v22
	v_lshlrev_b32_e32 v13, 16, v10
	v_lshlrev_b32_e32 v107, 16, v16
	v_and_b32_e32 v109, 0xffff0000, v16
	v_and_b32_e32 v94, 0xffff0000, v20
	v_lshlrev_b32_e32 v112, 16, v17
	v_lshlrev_b32_e32 v98, 16, v21
	v_and_b32_e32 v113, 0xffff0000, v17
	v_lshlrev_b32_e32 v115, 16, v18
	v_lshlrev_b32_e32 v116, 16, v2
	v_pk_mul_f32 v[16:17], v[24:25], v[26:27]
	v_pk_mul_f32 v[0:1], v[0:1], v[4:5]
	v_pk_mul_f32 v[4:5], v[8:9], v[12:13]
	v_pk_mul_f32 v[20:21], v[64:65], v[94:95]
	v_pk_mul_f32 v[24:25], v[96:97], v[98:99]
	v_mul_f32_e32 v65, v113, v114
	v_mul_f32_e32 v94, v115, v116
	v_mul_f32_e32 v107, v107, v108
	v_mul_f32_e32 v108, v109, v110
	v_mul_f32_e32 v64, v112, v111
	v_and_b32_e32 v18, 0xffff0000, v18
	v_and_b32_e32 v2, 0xffff0000, v2
	v_mul_f32_e32 v2, v18, v2
	s_waitcnt vmcnt(5)
	v_mov_b32_e32 v8, v70
	s_waitcnt vmcnt(4)
	v_mov_b32_e32 v13, v76
	v_mov_b32_e32 v76, v73
	s_waitcnt vmcnt(3)
	v_mov_b32_e32 v26, v78
	s_waitcnt vmcnt(2)
	v_mov_b32_e32 v27, v82
	v_mov_b32_e32 v9, v74
	v_mov_b32_e32 v74, v71
	v_mov_b32_e32 v12, v72
	v_pk_mul_f32 v[0:1], v[0:1], v[76:77]
	v_pk_mul_f32 v[4:5], v[4:5], v[26:27]
	v_pk_mul_f32 v[8:9], v[16:17], v[8:9]
	v_pk_mul_f32 v[16:17], v[20:21], v[74:75]
	v_pk_mul_f32 v[12:13], v[24:25], v[12:13]
	s_waitcnt vmcnt(1)
	v_fma_f32 v0, v65, v89, v0
	s_waitcnt vmcnt(0)
	v_fma_f32 v4, v94, v90, v4
	v_fma_f32 v8, v107, v86, v8
	v_fma_f32 v16, v108, v87, v16
	v_fma_f32 v12, v64, v88, v12
	v_add_f32_e32 v0, v0, v1
	v_add_f32_e32 v1, v4, v5
	v_add_f32_e32 v8, v8, v9
	v_add_f32_e32 v9, v16, v17
	v_add_f32_e32 v12, v12, v13
	v_mul_f32_e32 v13, v0, v102
	v_mul_f32_e32 v16, v1, v103
	v_and_b32_e32 v1, 0xffff0000, v6
	v_and_b32_e32 v0, 0xffff0000, v14
	v_and_b32_e32 v5, 0xffff0000, v10
	v_and_b32_e32 v4, 0xffff0000, v22
	v_pk_mul_f32 v[0:1], v[0:1], v[4:5]
	v_mov_b32_e32 v82, v79
	v_pk_mul_f32 v[0:1], v[0:1], v[82:83]
	v_lshlrev_b32_e32 v4, 16, v23
	v_fma_f32 v0, v2, v91, v0
	v_add_f32_e32 v0, v0, v1
	v_mul_f32_e32 v6, v0, v104
	v_lshlrev_b32_e32 v0, 16, v3
	v_lshlrev_b32_e32 v1, 16, v19
	v_mul_f32_e32 v2, v1, v0
	v_lshlrev_b32_e32 v0, 16, v15
	v_lshlrev_b32_e32 v1, 16, v7
	v_lshlrev_b32_e32 v5, 16, v11
	v_pk_mul_f32 v[0:1], v[0:1], v[4:5]
	v_mov_b32_e32 v4, v80
	v_mov_b32_e32 v5, v84
	v_pk_mul_f32 v[0:1], v[0:1], v[4:5]
	v_mov_b32_e32 v84, v81
	v_fma_f32 v0, v2, v92, v0
	v_add_f32_e32 v0, v0, v1
	v_mul_f32_e32 v4, v0, v105
	v_and_b32_e32 v0, 0xffff0000, v19
	v_and_b32_e32 v1, 0xffff0000, v3
	v_mul_f32_e32 v5, v0, v1
	v_and_b32_e32 v1, 0xffff0000, v7
	v_and_b32_e32 v0, 0xffff0000, v15
	v_and_b32_e32 v3, 0xffff0000, v11
	v_and_b32_e32 v2, 0xffff0000, v23
	v_pk_mul_f32 v[0:1], v[0:1], v[2:3]
	v_mul_f32_e32 v8, v8, v69
	v_pk_mul_f32 v[0:1], v[0:1], v[84:85]
	v_mul_f32_e32 v9, v9, v100
	v_fma_f32 v0, v5, v93, v0
	v_add_f32_e32 v0, v0, v1
	v_mul_f32_e32 v3, v0, v106
	v_mul_f32_e32 v12, v12, v101
	v_cvt_pk_bf16_f32 v0, v8, v9
	v_cvt_pk_bf16_f32 v1, v12, v13
	v_cvt_pk_bf16_f32 v2, v16, v6
	v_cvt_pk_bf16_f32 v3, v4, v3
	v_add_co_u32_e32 v4, vcc, s13, v28
	v_lshl_add_u64 v[18:19], s[30:31], 0, v[58:59]
	s_nop 0
	v_addc_co_u32_e32 v5, vcc, 0, v29, vcc
	global_store_dwordx4 v[4:5], v[0:3], off offset:1024
	v_lshl_add_u64 v[20:21], s[30:31], 0, v[60:61]
	s_nop 0
	s_nop 1
	v_and_b32_e32 v28, 0xffff0000, v176
	v_and_b32_e32 v0, 64, v30
	v_xor_b32_e32 v1, 1, v30
	v_add_u32_e32 v26, 64, v0
	v_cmp_lt_i32_e32 vcc, v1, v26
	v_lshlrev_b32_e32 v27, 16, v176
	v_lshlrev_b32_e32 v29, 16, v177
	v_cndmask_b32_e32 v0, v30, v1, vcc
	v_mul_f32_e32 v1, v28, v28
	v_fmac_f32_e32 v1, v27, v27
	v_and_b32_e32 v64, 0xffff0000, v177
	v_fmac_f32_e32 v1, v29, v29
	v_lshlrev_b32_e32 v65, 16, v178
	v_fmac_f32_e32 v1, v64, v64
	v_and_b32_e32 v69, 0xffff0000, v178
	v_fmac_f32_e32 v1, v65, v65
	v_lshlrev_b32_e32 v70, 16, v179
	v_fmac_f32_e32 v1, v69, v69
	v_and_b32_e32 v71, 0xffff0000, v179
	v_fmac_f32_e32 v1, v70, v70
	v_fmac_f32_e32 v1, v71, v71
	v_lshlrev_b32_e32 v0, 2, v0
	v_lshlrev_b32_e32 v24, 16, v180
	v_and_b32_e32 v25, 0xffff0000, v180
	v_pk_mul_f32 v[2:3], v[24:25], v[24:25]
	v_lshlrev_b32_e32 v22, 16, v181
	v_and_b32_e32 v23, 0xffff0000, v181
	v_add_f32_e32 v1, v1, v2
	v_pk_mul_f32 v[4:5], v[22:23], v[22:23]
	v_add_f32_e32 v1, v1, v3
	v_add_f32_e32 v1, v1, v4
	v_add_f32_e32 v1, v1, v5
	ds_bpermute_b32 v2, v0, v1
	v_xor_b32_e32 v3, 2, v30
	v_cmp_lt_i32_e32 vcc, v3, v26
	v_xor_b32_e32 v4, 4, v30
	v_xor_b32_e32 v5, 8, v30
	v_cndmask_b32_e32 v3, v30, v3, vcc
	v_lshlrev_b32_e32 v3, 2, v3
	s_waitcnt lgkmcnt(0)
; __device__ __forceinline__ unsigned pk2(float lo, float hi) { return pg8::cvt_pk_bf16(lo, hi); }
; __device__ __forceinline__ float bf2f(bf16 h) { return __uint_as_float((unsigned)h << 16); }
; __device__ __forceinline__ v4u pack8f(const float (&f)[8]) { v4u o; o.x = pk2(f[0], f[1]); o.y = pk2(f[2], f[3]); o.z = pk2(f[4], f[5]); o.w = pk2(f[6], f[7]); return o; }
; __global__ void __launch_bounds__(NWAVES * 64, 2) fwd_kernel(Args a) {
;     ...
;                 float s = 0.f;
; #pragma unroll
;                 for (int e = 0; e < 8; ++e) s += fa[e] * fa[e];
; #pragma unroll
;                 for (int e = 0; e < 4; ++e) s += fb4[e] * fb4[e];
;                 const float r = rsqrtf(wave_sum(s) * (1.f / 768.f) + EPS);
;                 const f32x4 g0 = *(const f32x4*)(qg + lane * 8), g1 = *(const f32x4*)(qg + lane * 8 + 4), g2 = *(const f32x4*)(qg + 512 + lane * 4);
;                 float oa[8] = {fa[0] * r * g0.x, fa[1] * r * g0.y, fa[2] * r * g0.z, fa[3] * r * g0.w, fa[4] * r * g1.x, fa[5] * r * g1.y, fa[6] * r * g1.z, fa[7] * r * g1.w};
;                 *(v4u*)(qn + (size_t)m * QL + lane * 8) = pack8f(oa);
;                 v2u ob; ob.x = pk2(fb4[0] * r * g2.x, fb4[1] * r * g2.y); ob.y = pk2(fb4[2] * r * g2.z, fb4[3] * r * g2.w);
;                 *(v2u*)(qn + (size_t)m * QL + 512 + lane * 4) = ob;
;             }
;             {
;                 const float ang = (float)positions[m] * ifq; const double rev = (double)ang * 0.15915494309189535; const float frc = (float)(rev - __builtin_floor(rev));
;                 const float cs = __builtin_amdgcn_cosf(frc), sn = __builtin_amdgcn_sinf(frc);
;                 if (lane < 32) { cst[(size_t)m * 32 + lane] = cs; snt[(size_t)m * 32 + lane] = sn; }
;                 const float kr = bf2f(zkr[(size_t)m * 64 + lane]); const float kss = wave_sum(kr * kr); if (lane == 0) krss[m] = kss;
;                 const float v = kr * gkr, pt = __shfl_xor(v, 32);
	v_add_f32_e32 v1, v1, v2
	ds_bpermute_b32 v2, v3, v1
	v_cmp_lt_i32_e32 vcc, v4, v26
	s_waitcnt lgkmcnt(0)
	v_add_f32_e32 v1, v1, v2
	v_cndmask_b32_e32 v4, v30, v4, vcc
	v_lshlrev_b32_e32 v4, 2, v4
	ds_bpermute_b32 v2, v4, v1
	v_cmp_lt_i32_e32 vcc, v5, v26
	s_waitcnt lgkmcnt(0)
	v_add_f32_e32 v2, v1, v2
	v_cndmask_b32_e32 v5, v30, v5, vcc
	v_lshlrev_b32_e32 v5, 2, v5
	ds_bpermute_b32 v72, v5, v2
	v_xor_b32_e32 v1, 16, v30
	v_cmp_lt_i32_e32 vcc, v1, v26
	s_waitcnt lgkmcnt(0)
	v_add_f32_e32 v72, v2, v72
	v_cndmask_b32_e32 v1, v30, v1, vcc
	v_lshlrev_b32_e32 v1, 2, v1
	ds_bpermute_b32 v73, v1, v72
	v_xor_b32_e32 v2, 32, v30
	v_cmp_lt_i32_e32 vcc, v2, v26
	s_waitcnt lgkmcnt(0)
	v_add_f32_e32 v26, v72, v73
	v_cndmask_b32_e32 v2, v30, v2, vcc
	v_lshlrev_b32_e32 v2, 2, v2
	ds_bpermute_b32 v72, v2, v26
	s_waitcnt lgkmcnt(0)
	v_add_f32_e32 v26, v26, v72
	v_fmamk_f32 v26, v26, 0x3aaaaaab, v68
	v_mul_f32_e32 v72, 0x4b800000, v26
	v_cmp_gt_f32_e32 vcc, s34, v26
	s_nop 1
	v_cndmask_b32_e32 v26, v26, v72, vcc
	v_rsq_f32_e32 v26, v26
	s_nop 0
	v_mul_f32_e32 v72, 0x45800000, v26
	v_cndmask_b32_e32 v26, v26, v72, vcc
	v_mul_f32_e32 v27, v26, v27
	v_mul_f32_e32 v65, v26, v65
	v_mul_f32_e32 v28, v26, v28
	v_mul_f32_e32 v10, v188, v27
	v_mul_f32_e32 v27, v184, v65
	v_mul_f32_e32 v6, v26, v69
	v_mul_f32_e32 v29, v26, v29
	v_mul_f32_e32 v11, v189, v28
	v_mul_f32_e32 v28, v185, v6
	v_mul_f32_e32 v6, v26, v70
	v_mul_f32_e32 v12, v190, v29
	v_mul_f32_e32 v29, v186, v6
	v_mul_f32_e32 v6, v26, v71
	v_mul_f32_e32 v64, v26, v64
	v_mul_f32_e32 v9, v187, v6
	v_cvt_pk_bf16_f32 v6, v10, v11
	v_add_co_u32_e32 v10, vcc, s35, v18
	v_mul_f32_e32 v13, v191, v64
	v_cvt_pk_bf16_f32 v7, v12, v13
	s_nop 0
	v_addc_co_u32_e32 v11, vcc, 0, v19, vcc
	v_cvt_pk_bf16_f32 v8, v27, v28
	v_cvt_pk_bf16_f32 v9, v29, v9
	global_store_dwordx4 v[10:11], v[6:9], off
	s_nop 1
	v_mul_f32_e32 v6, v26, v24
	v_mul_f32_e32 v7, v26, v25
	v_mul_f32_e32 v6, v192, v6
	v_mul_f32_e32 v7, v193, v7
	v_cvt_pk_bf16_f32 v6, v6, v7
	v_mul_f32_e32 v7, v26, v22
	v_mul_f32_e32 v8, v26, v23
	v_mul_f32_e32 v7, v194, v7
	v_mul_f32_e32 v8, v195, v8
	v_cvt_pk_bf16_f32 v7, v7, v8
	v_add_co_u32_e32 v8, vcc, s35, v20
	s_nop 1
	v_addc_co_u32_e32 v9, vcc, 0, v21, vcc
	global_store_dwordx2 v[8:9], v[6:7], off offset:1024
	v_cvt_f32_i32_e32 v6, v182
	v_mul_f32_e32 v6, v66, v6
	v_cvt_f64_f32_e32 v[6:7], v6
	v_mul_f64 v[8:9], v[6:7], s[56:57]
	v_floor_f64_e32 v[8:9], v[8:9]
	v_fma_f64 v[6:7], v[6:7], s[56:57], -v[8:9]
	v_cvt_f32_f64_e32 v7, v[6:7]
	v_cos_f32_e32 v6, v7
	v_sin_f32_e32 v7, v7
	s_and_saveexec_b64 s[4:5], s[0:1]
	s_cbranch_execz .LBB0_283
	v_lshl_add_u64 v[8:9], s[30:31], 0, v[56:57]
	v_add_co_u32_e32 v10, vcc, 0x15600000, v8
	s_nop 1
	v_addc_co_u32_e32 v11, vcc, 0, v9, vcc
	v_add_co_u32_e32 v8, vcc, 0x15700000, v8
	global_store_dword v[10:11], v6, off
	s_nop 0
	v_addc_co_u32_e32 v9, vcc, 0, v9, vcc
	global_store_dword v[8:9], v7, off
.LBB0_283:
	s_or_b64 exec, exec, s[4:5]
	v_lshlrev_b32_e32 v8, 16, v183
	v_mul_f32_e32 v9, v8, v8
	ds_bpermute_b32 v9, v0, v9
	s_waitcnt lgkmcnt(0)
	v_fmac_f32_e32 v9, v8, v8
	ds_bpermute_b32 v10, v3, v9
	s_waitcnt lgkmcnt(0)
	v_add_f32_e32 v9, v9, v10
	ds_bpermute_b32 v10, v4, v9
	s_waitcnt lgkmcnt(0)
	v_add_f32_e32 v9, v9, v10
	ds_bpermute_b32 v10, v5, v9
	s_waitcnt lgkmcnt(0)
	v_add_f32_e32 v9, v9, v10
	ds_bpermute_b32 v10, v1, v9
	s_waitcnt lgkmcnt(0)
	v_add_f32_e32 v9, v9, v10
	ds_bpermute_b32 v10, v2, v9
	s_and_saveexec_b64 s[4:5], s[8:9]
	s_cbranch_execz .LBB0_263
	s_add_u32 s6, s30, s24
	s_addc_u32 s7, s31, s25
	s_waitcnt lgkmcnt(0)
	v_add_f32_e32 v9, v9, v10
	global_store_dword v31, v9, s[6:7]
	s_branch .LBB0_263
